# NSA work queue: next ticket atomic issued at the start of the unit's tail section (overlaps the OACC/store section), pop waits vmcnt(8) past the 8 output stores instead of vmcnt(0); first pop still bl
# speedup vs baseline: 1.0189x; 1.0025x over previous
; #define LAS __attribute__((address_space(3)))
; __device__ __forceinline__ void nsa_unit(const Args& a, int l, int b, int qi, float bnd0, float bnd1, float bnd2, LAS unsigned char* lds, int tid, int lane, int wave) {
;     LAS bf16_t* KVB = (LAS bf16_t*)lds;
;     LAS float* IMP = (LAS float*)(lds + 37888);
;     LAS unsigned long long* SELM = (LAS unsigned long long*)(lds + 104448);
;     LAS float* INVL = (LAS float*)(lds + 105024);
;     const bf16_t* QN = (const bf16_t*)(a.ws + WS_QN); const float* GATES = (const float*)(a.ws + WS_GATES); bf16_t* Y = (bf16_t*)(a.ws + WS_Y);
;     const int fr = lane & 15, fq = lane >> 4, h = wave >> 1, qbase = (wave & 1) * 32;
;     const size_t t0 = (size_t)b * SEQ + 64 * qi;
;     const float slope2 = LOG2E * exp2f(-2.0f * (float)(h + 1));
;     bf16x8 qf[2][2]; float gate[2][3];
; #pragma unroll
;     for (int mt = 0; mt < 2; ++mt) { const size_t t = t0 + qbase + 16 * mt + fr;
; #pragma unroll
;         for (int ks = 0; ks < 2; ++ks) qf[mt][ks] = *(const bf16x8*)(QN + t * 256 + h * 64 + 32 * ks + 8 * fq);
; #pragma unroll
;         for (int br = 0; br < 3; ++br) gate[mt][br] = GATES[t * 12 + h * 3 + br]; }
; __device__ __forceinline__ void nsa_phase(const Args& a, int l, int qslot, LAS unsigned char* lds, int tid, int lane, int wave) {
;     unsigned* ctr = (unsigned*)(a.ws + WS_CTL) + 64 * qslot;
;     LAS int* slot = (LAS int*)(lds + 106048);
;     const float qmx = wave_max64(fabsf(INTAB(a)[20][l * 64 + lane]));
;     const float bnd0 = 11.72f * qmx * wave_max64(fabsf(INTAB(a)[21][l * 192 + lane])), bnd1 = 11.72f * qmx * wave_max64(fabsf(INTAB(a)[21][l * 192 + 64 + lane])), bnd2 = 11.72f * qmx * wave_max64(fabsf(INTAB(a)[21][l * 192 + 128 + lane]));
.LBB0_128:
	s_waitcnt vmcnt(0)
	v_mov_b32_e32 v8, v228
	v_readlane_b32 s15, v252, 0
	v_readlane_b32 s38, v252, 13
	v_readlane_b32 s15, v254, 46
	v_readlane_b32 s39, v252, 14
	v_and_b32_e32 v0, 64, v234
	v_xor_b32_e32 v2, 1, v234
	v_add_u32_e32 v0, 64, v0
	s_waitcnt lgkmcnt(0)
	v_xor_b32_e32 v9, 2, v234
	global_load_dwordx4 v[10:13], v1, s[38:39]
	s_lshl_b32 s38, s9, 7
	v_cmp_lt_i32_e32 vcc, v2, v0
	v_xor_b32_e32 v14, 4, v234
	s_ashr_i32 s39, s38, 31
	v_readfirstlane_b32 s15, v8
	v_cndmask_b32_e32 v2, v234, v2, vcc
	v_cmp_lt_i32_e32 vcc, v9, v0
	v_xor_b32_e32 v15, 8, v234
	s_lshl_b64 s[38:39], s[38:39], 2
	v_cndmask_b32_e32 v9, v234, v9, vcc
	v_cmp_lt_i32_e32 vcc, v14, v0
	s_ashr_i32 s23, s15, 6
	v_xor_b32_e32 v16, 16, v234
	v_and_b32_e32 v129, 63, v8
	v_cndmask_b32_e32 v18, v234, v14, vcc
	v_cmp_lt_i32_e32 vcc, v15, v0
	s_add_u32 s38, s72, s38
	v_xor_b32_e32 v17, 32, v234
	s_mul_i32 s40, s9, 0xc0
	v_cndmask_b32_e32 v19, v234, v15, vcc
	v_cmp_lt_i32_e32 vcc, v16, v0
	v_lshl_or_b32 v14, s9, 6, v129
	s_addc_u32 s39, s73, s39
	v_cndmask_b32_e32 v20, v234, v16, vcc
	v_cmp_lt_i32_e32 vcc, v17, v0
	v_or_b32_e32 v16, s40, v129
	v_ashrrev_i32_e32 v15, 31, v14
	v_writelane_b32 v255, s38, 9
	v_cndmask_b32_e32 v0, v234, v17, vcc
	v_ashrrev_i32_e32 v17, 31, v16
	v_writelane_b32 v255, s39, 10
	s_ashr_i32 s38, s40, 31
	s_movk_i32 s40, 0x1040
	v_cmp_gt_i32_e64 s[40:41], s40, v8
	v_ashrrev_i32_e32 v133, 3, v8
	v_lshlrev_b32_e32 v162, 2, v0
	v_writelane_b32 v255, s40, 11
	v_mov_b32_e32 v21, 0x980
	v_bfe_u32 v131, v8, 4, 2
	v_writelane_b32 v255, s41, 12
	s_movk_i32 s40, 0x48
	v_mul_lo_u32 v0, v133, s40
	s_movk_i32 s40, 0x90
	s_ashr_i32 s41, s15, 7
	v_lshlrev_b32_e32 v172, 1, v0
	s_add_i32 s44, s41, 1
	s_lshl_b32 s9, s23, 5
	s_mul_i32 s49, s41, 0x4100
	v_lshlrev_b32_e32 v9, 2, v9
	v_lshlrev_b32_e32 v18, 2, v18
	v_lshlrev_b32_e32 v19, 2, v19
	v_lshlrev_b32_e32 v139, 2, v20
	s_mul_i32 s46, s41, 3
	v_lshlrev_b32_e32 v22, 2, v129
	v_lshlrev_b32_e32 v20, 3, v131
	v_lshlrev_b32_e32 v164, 1, v133
	v_mov_b32_e32 v3, v1
	v_mov_b32_e32 v123, v1
	v_lshlrev_b32_e32 v128, 2, v131
	v_cmp_gt_u32_e64 s[42:43], 16, v129
	v_add_u32_e32 v186, 0xfffffe00, v8
	v_lshlrev_b32_e32 v188, 1, v20
	s_waitcnt vmcnt(0)
	v_lshl_add_u64 v[10:11], v[14:15], 2, v[10:11]
	flat_load_dword v14, v[10:11]
	v_lshl_add_u64 v[10:11], v[16:17], 2, v[12:13]
	v_mov_b32_e32 v17, s38
	flat_load_dword v15, v[10:11]
	v_lshl_add_u64 v[10:11], v[16:17], 2, v[12:13]
	flat_load_dword v12, v[10:11] offset:256
	v_and_b32_e32 v13, 15, v8
	flat_load_dword v10, v[10:11] offset:512
	v_lshlrev_b32_e32 v11, 3, v8
	v_lshlrev_b32_e32 v17, 2, v2
	v_and_b32_e32 v2, 56, v11
	v_mov_b32_e32 v11, 0x900
	v_mad_u32_u24 v166, v13, s40, v11
	v_mov_b32_e32 v11, 0x1200
	v_mad_u32_u24 v167, v13, s40, v11
	s_movk_i32 s40, 0x98
	v_lshlrev_b32_e32 v0, 1, v2
	v_mad_u32_u24 v169, v13, s40, v21
	v_mov_b32_e32 v21, 0x1300
	v_add3_u32 v175, 0, v172, v0
	v_cvt_f32_i32_e32 v0, s44
	v_or_b32_e32 v11, 48, v129
	v_mad_u32_u24 v170, v13, s40, v21
	v_lshlrev_b32_e32 v21, 6, v131
	v_mul_u32_u24_e32 v173, 0x90, v11
	v_mul_u32_u24_e32 v174, 0x98, v11
	v_sub_u32_e32 v11, v13, v21
	s_and_b32 s40, s9, 32
	v_or_b32_e32 v11, s40, v11
	v_subrev_u32_e32 v178, 31, v11
	v_mul_f32_e32 v11, -2.0, v0
	s_mov_b32 s44, 0xc2fc0000
	v_cmp_gt_f32_e32 vcc, s44, v11
	v_mov_b32_e32 v11, 0x42800000
	s_and_b64 s[44:45], vcc, exec
	v_cndmask_b32_e32 v11, 0, v11, vcc
	v_fmac_f32_e32 v11, -2.0, v0
	v_exp_f32_e32 v0, v11
	s_cselect_b32 s44, 0xffffffc0, 0
	s_add_i32 s45, s49, 0
	v_or_b32_e32 v130, s40, v13
	v_mov_b32_e32 v11, s45
	s_movk_i32 s45, 0x104
	v_ldexp_f32 v0, v0, s44
	v_mul_u32_u24_e32 v23, 0x4c, v2
	v_mad_u32_u24 v179, v130, s45, v11
	v_mul_f32_e32 v134, 0x3fb8aa3b, v0
	v_lshlrev_b32_e32 v176, 1, v23
	s_lshl_b32 s48, s41, 6
	s_lshl_b32 s41, s41, 8
	s_lshl_b32 s50, s40, 2
	s_add_i32 s41, s41, 0
	s_add_i32 s41, s41, s50
	s_add_i32 s41, s41, 0x19a40
	v_add_u32_e32 v180, s41, v22
	s_add_i32 s41, 0, 0x19800
	s_lshl_b32 s50, s23, 3
	s_lshl_b32 s40, s40, 3
	s_ashr_i32 s49, s48, 31
	s_add_i32 s14, s41, s50
	s_add_i32 s41, s41, s40
	s_ashr_i32 s47, s46, 31
	v_lshl_add_u32 v184, v13, 3, s41
	s_lshl_b64 s[80:81], s[48:49], 1
	v_readlane_b32 s40, v252, 17
	v_readlane_b32 s41, v252, 18
	s_add_u32 s40, s40, s80
	s_addc_u32 s41, s41, s81
	v_lshlrev_b32_e32 v16, 4, v8
	v_add_u32_e32 v163, 0, v16
	v_mul_f32_e32 v136, 0x41800000, v134
	v_writelane_b32 v255, s14, 13
	s_mulk_i32 s23, 0x820
	v_cmp_eq_u32_e64 s[38:39], 0, v8
	v_mul_u32_u24_e32 v165, 0x90, v13
	v_mul_u32_u24_e32 v168, 0x98, v13
	v_add_u32_e32 v171, 0x9400, v163
	v_add3_u32 v177, 0, v176, v164
	v_or_b32_e32 v132, 16, v130
	v_cmp_eq_u32_e64 s[44:45], 0, v129
	s_waitcnt vmcnt(0) lgkmcnt(0)
; __device__ __forceinline__ float wave_max64(float v) {
; #pragma unroll
;     for (int o = 1; o < 64; o <<= 1) v = fmaxf(v, __shfl_xor(v, o));
;     return v;
; }
; __device__ __forceinline__ void nsa_phase(const Args& a, int l, int qslot, LAS unsigned char* lds, int tid, int lane, int wave) {
;     ...
;     const float qmx = wave_max64(fabsf(INTAB(a)[20][l * 64 + lane]));
;     const float bnd0 = 11.72f * qmx * wave_max64(fabsf(INTAB(a)[21][l * 192 + lane])), bnd1 = 11.72f * qmx * wave_max64(fabsf(INTAB(a)[21][l * 192 + 64 + lane])), bnd2 = 11.72f * qmx * wave_max64(fabsf(INTAB(a)[21][l * 192 + 128 + lane]));
;     for (;;) {
	v_and_b32_e32 v0, 0x7fffffff, v14
	v_max_f32_e64 v11, |v14|, |v14|
	ds_bpermute_b32 v0, v17, v0
	v_and_b32_e32 v14, 0x7fffffff, v15
	ds_bpermute_b32 v14, v17, v14
	v_and_b32_e32 v21, 0x7fffffff, v12
	ds_bpermute_b32 v21, v17, v21
	v_and_b32_e32 v23, 0x7fffffff, v10
	ds_bpermute_b32 v17, v17, v23
	v_max_f32_e64 v15, |v15|, |v15|
	s_waitcnt lgkmcnt(3)
	v_max_f32_e32 v0, v0, v0
	s_waitcnt lgkmcnt(2)
	v_max_f32_e32 v14, v14, v14
	v_max_f32_e64 v12, |v12|, |v12|
	v_max_f32_e64 v10, |v10|, |v10|
	v_max_f32_e32 v0, v11, v0
	v_max_f32_e32 v11, v15, v14
	s_waitcnt lgkmcnt(1)
	v_max_f32_e32 v14, v21, v21
	s_waitcnt lgkmcnt(0)
	v_max_f32_e32 v15, v17, v17
	ds_bpermute_b32 v17, v9, v0
	v_max_f32_e32 v12, v12, v14
	v_max_f32_e32 v10, v10, v15
	ds_bpermute_b32 v21, v9, v11
	ds_bpermute_b32 v14, v9, v12
	ds_bpermute_b32 v9, v9, v10
	s_waitcnt lgkmcnt(3)
	v_max_f32_e32 v15, v17, v17
	v_max_f32_e32 v0, v0, v15
	s_waitcnt lgkmcnt(2)
	v_max_f32_e32 v17, v21, v21
	s_waitcnt lgkmcnt(1)
	v_max_f32_e32 v14, v14, v14
	s_waitcnt lgkmcnt(0)
	v_max_f32_e32 v9, v9, v9
	v_max_f32_e32 v11, v11, v17
	ds_bpermute_b32 v15, v18, v0
	v_max_f32_e32 v12, v12, v14
	v_max_f32_e32 v9, v10, v9
	ds_bpermute_b32 v17, v18, v11
	ds_bpermute_b32 v10, v18, v12
	ds_bpermute_b32 v14, v18, v9
	s_waitcnt lgkmcnt(3)
	v_max_f32_e32 v15, v15, v15
	v_max_f32_e32 v0, v0, v15
	s_waitcnt lgkmcnt(2)
	v_max_f32_e32 v17, v17, v17
	s_waitcnt lgkmcnt(1)
	v_max_f32_e32 v10, v10, v10
	s_waitcnt lgkmcnt(0)
	v_max_f32_e32 v14, v14, v14
	v_max_f32_e32 v11, v11, v17
	ds_bpermute_b32 v15, v19, v0
	v_max_f32_e32 v10, v12, v10
	v_max_f32_e32 v9, v9, v14
	ds_bpermute_b32 v17, v19, v11
	ds_bpermute_b32 v12, v19, v10
	ds_bpermute_b32 v14, v19, v9
	s_waitcnt lgkmcnt(3)
	v_max_f32_e32 v15, v15, v15
	v_max_f32_e32 v0, v0, v15
	s_waitcnt lgkmcnt(2)
	v_max_f32_e32 v17, v17, v17
	s_waitcnt lgkmcnt(1)
	v_max_f32_e32 v12, v12, v12
	s_waitcnt lgkmcnt(0)
	v_max_f32_e32 v14, v14, v14
	v_max_f32_e32 v11, v11, v17
	ds_bpermute_b32 v15, v139, v0
	v_max_f32_e32 v10, v10, v12
	v_max_f32_e32 v9, v9, v14
	ds_bpermute_b32 v17, v139, v11
	ds_bpermute_b32 v12, v139, v10
	ds_bpermute_b32 v14, v139, v9
	s_waitcnt lgkmcnt(3)
	v_max_f32_e32 v15, v15, v15
	v_max_f32_e32 v0, v0, v15
	s_waitcnt lgkmcnt(2)
	v_max_f32_e32 v17, v17, v17
	s_waitcnt lgkmcnt(1)
	v_max_f32_e32 v12, v12, v12
	s_waitcnt lgkmcnt(0)
	v_max_f32_e32 v14, v14, v14
	v_max_f32_e32 v11, v11, v17
	ds_bpermute_b32 v15, v162, v0
	v_max_f32_e32 v10, v10, v12
	v_max_f32_e32 v9, v9, v14
	ds_bpermute_b32 v17, v162, v11
	ds_bpermute_b32 v12, v162, v10
	ds_bpermute_b32 v14, v162, v9
	s_waitcnt lgkmcnt(3)
	v_max_f32_e32 v15, v15, v15
	v_max_f32_e32 v0, v0, v15
	s_waitcnt lgkmcnt(2)
	v_max_f32_e32 v17, v17, v17
	s_waitcnt lgkmcnt(1)
	v_max_f32_e32 v12, v12, v12
	s_waitcnt lgkmcnt(0)
	v_max_f32_e32 v14, v14, v14
	v_max_f32_e32 v11, v11, v17
	v_mul_f32_e32 v0, 0x413b851f, v0
	v_max_f32_e32 v10, v10, v12
	v_max_f32_e32 v9, v9, v14
	v_mul_f32_e32 v181, v0, v11
	v_mul_f32_e32 v182, v0, v10
	v_mul_f32_e32 v183, v0, v9
	v_and_b32_e32 v0, 48, v8
	v_lshl_add_u64 v[140:141], s[40:41], 0, v[0:1]
	s_lshl_b64 s[40:41], s[46:47], 2
	s_add_u32 s82, s60, s40
	s_addc_u32 s83, s61, s41
	s_andn2_b32 s15, s15, 63
	v_lshlrev_b64 v[10:11], v8, -1
	s_add_i32 s40, 0, 0x9400
	s_add_i32 s14, s15, 0x19800
	v_not_b32_e32 v127, v11
	v_not_b32_e32 v138, v10
	v_mov_b32_e32 v142, v136
	v_mov_b32_e32 v143, v136
	v_mov_b32_e32 v144, v136
	v_mov_b32_e32 v145, v136
	v_mov_b32_e32 v146, v134
	v_mov_b32_e32 v147, v134
	v_mov_b32_e32 v148, v134
	v_mov_b32_e32 v149, v134
	v_add_u32_e32 v185, s40, v16
	v_writelane_b32 v255, s14, 14
	v_add_u32_e32 v187, s23, v22
	v_mov_b32_e32 v249, -1
	s_branch .LBB0_132

; __device__ __forceinline__ unsigned pk2(float lo, float hi) { return pg8::cvt_pk_bf16(lo, hi); }
; __device__ __forceinline__ void nsa_unit(const Args& a, int l, int b, int qi, float bnd0, float bnd1, float bnd2, LAS unsigned char* lds, int tid, int lane, int wave) {
;     ...
; #pragma unroll
;     for (int mt = 0; mt < 2; ++mt) { float lt = lrow[mt]; lt += __shfl_xor(lt, 16); lt += __shfl_xor(lt, 32); const float sc = lt > 0.f ? gate[mt][2] / lt : 0.f;
;         const size_t t = t0 + qbase + 16 * mt + fr;
; #pragma unroll
;         for (int dt = 0; dt < 4; ++dt) { const f32x4 r = OACC[(mt * 4 + dt) * 512] + o[mt][dt] * sc;
;             u32x2 w; w.x = pk2(r[0], r[1]); w.y = pk2(r[2], r[3]);
;             *(u32x2*)(Y + t * D + 512 + h * 64 + 16 * dt + 4 * fq) = w; } }
;     __syncthreads();
.LBB0_130:
	s_and_saveexec_b64 s[50:51], s[38:39]
	s_cbranch_execz .Lq_pf_skip
	v_readlane_b32 s48, v255, 9
	v_readlane_b32 s49, v255, 10
	s_nop 4
	global_atomic_add v249, v1, v250, s[48:49] sc0
.Lq_pf_skip:
	s_or_b64 exec, exec, s[50:51]
	ds_bpermute_b32 v0, v139, v93
	v_lshlrev_b64 v[8:9], 11, v[152:153]
	s_waitcnt lgkmcnt(0)
	v_lshl_add_u64 v[8:9], s[72:73], 0, v[8:9]
	v_mov_b32_e32 v155, v1
	v_lshl_add_u64 v[8:9], v[8:9], 0, s[80:81]
	v_add_f32_e32 v0, v93, v0
	ds_bpermute_b32 v10, v162, v0
	v_lshl_add_u64 v[12:13], v[8:9], 0, v[154:155]
	s_mov_b32 s15, 0x1b800000
	s_mov_b64 s[46:47], 0x1b800400
	s_waitcnt lgkmcnt(0)
	v_add_f32_e32 v0, v0, v10
	v_div_scale_f32 v10, s[40:41], v0, v0, v126
	v_rcp_f32_e32 v11, v10
	v_div_scale_f32 v8, vcc, v126, v0, v126
	v_fma_f32 v9, -v10, v11, 1.0
	v_fmac_f32_e32 v11, v9, v11
	v_mul_f32_e32 v9, v8, v11
	v_fma_f32 v14, -v10, v9, v8
	v_fmac_f32_e32 v9, v14, v11
	v_fma_f32 v8, -v10, v9, v8
	v_div_fmas_f32 v8, v8, v11, v9
	v_div_fixup_f32 v8, v8, v0, v126
	v_cmp_lt_f32_e32 vcc, 0, v0
	s_nop 1
	v_cndmask_b32_e32 v0, 0, v8, vcc
	v_pk_fma_f32 v[8:9], v[54:55], v[0:1], v[58:59] op_sel_hi:[1,0,1]
	v_pk_fma_f32 v[10:11], v[52:53], v[0:1], v[56:57] op_sel_hi:[1,0,1]
	v_add_co_u32_e32 v16, vcc, s15, v12
	v_cvt_pk_bf16_f32 v14, v10, v11
	v_cvt_pk_bf16_f32 v15, v8, v9
	ds_read_b128 v[8:11], v163 offset:46080
	s_nop 0
	v_addc_co_u32_e32 v17, vcc, 0, v13, vcc
	global_store_dwordx2 v[16:17], v[14:15], off offset:1024
	ds_bpermute_b32 v16, v139, v92
	s_waitcnt lgkmcnt(1)
	v_pk_fma_f32 v[10:11], v[50:51], v[0:1], v[10:11] op_sel_hi:[1,0,1]
	v_pk_fma_f32 v[8:9], v[48:49], v[0:1], v[8:9] op_sel_hi:[1,0,1]
	v_lshl_add_u64 v[12:13], v[12:13], 0, s[46:47]
	v_cvt_pk_bf16_f32 v14, v8, v9
	v_cvt_pk_bf16_f32 v15, v10, v11
	ds_read_b128 v[8:11], v163 offset:54272
	s_waitcnt lgkmcnt(1)
	v_add_f32_e32 v16, v92, v16
	global_store_dwordx2 v[12:13], v[14:15], off offset:32
	ds_bpermute_b32 v17, v162, v16
	s_waitcnt lgkmcnt(1)
	v_pk_fma_f32 v[10:11], v[46:47], v[0:1], v[10:11] op_sel_hi:[1,0,1]
	v_pk_fma_f32 v[8:9], v[44:45], v[0:1], v[8:9] op_sel_hi:[1,0,1]
	s_nop 0
	v_cvt_pk_bf16_f32 v14, v8, v9
	v_cvt_pk_bf16_f32 v15, v10, v11
	ds_read_b128 v[8:11], v163 offset:62464
	global_store_dwordx2 v[12:13], v[14:15], off offset:64
	s_waitcnt lgkmcnt(0)
	v_pk_fma_f32 v[10:11], v[42:43], v[0:1], v[10:11] op_sel_hi:[1,0,1]
	v_pk_fma_f32 v[8:9], v[40:41], v[0:1], v[8:9] op_sel_hi:[1,0,1]
	v_add_f32_e32 v0, v16, v17
	v_div_scale_f32 v14, s[40:41], v0, v0, v122
	v_rcp_f32_e32 v15, v14
	v_cvt_pk_bf16_f32 v8, v8, v9
	v_cvt_pk_bf16_f32 v9, v10, v11
	global_store_dwordx2 v[12:13], v[8:9], off offset:96
	v_fma_f32 v8, -v14, v15, 1.0
	v_fmac_f32_e32 v15, v8, v15
	v_div_scale_f32 v8, vcc, v122, v0, v122
	v_mul_f32_e32 v9, v8, v15
	v_fma_f32 v10, -v14, v9, v8
	v_fmac_f32_e32 v9, v10, v15
	v_fma_f32 v8, -v14, v9, v8
	v_div_fmas_f32 v8, v8, v15, v9
	v_div_fixup_f32 v8, v8, v0, v122
	v_cmp_lt_f32_e32 vcc, 0, v0
	v_lshlrev_b64 v[12:13], 11, v[150:151]
	v_lshl_add_u64 v[12:13], s[72:73], 0, v[12:13]
	v_cndmask_b32_e32 v0, 0, v8, vcc
	ds_read_b128 v[8:11], v171 offset:32768
	v_lshl_add_u64 v[12:13], v[12:13], 0, s[80:81]
	v_lshl_add_u64 v[12:13], v[12:13], 0, v[154:155]
	v_add_co_u32_e32 v16, vcc, s15, v12
	s_waitcnt lgkmcnt(0)
	v_pk_fma_f32 v[10:11], v[38:39], v[0:1], v[10:11] op_sel_hi:[1,0,1]
	v_pk_fma_f32 v[8:9], v[36:37], v[0:1], v[8:9] op_sel_hi:[1,0,1]
	v_addc_co_u32_e32 v17, vcc, 0, v13, vcc
	v_cvt_pk_bf16_f32 v14, v8, v9
	v_cvt_pk_bf16_f32 v15, v10, v11
	ds_read_b128 v[8:11], v171 offset:40960
	global_store_dwordx2 v[16:17], v[14:15], off offset:1024
	v_lshl_add_u64 v[12:13], v[12:13], 0, s[46:47]
	s_mov_b64 s[46:47], 0
	s_waitcnt lgkmcnt(0)
	v_pk_fma_f32 v[10:11], v[34:35], v[0:1], v[10:11] op_sel_hi:[1,0,1]
	v_pk_fma_f32 v[8:9], v[32:33], v[0:1], v[8:9] op_sel_hi:[1,0,1]
	s_nop 0
	v_cvt_pk_bf16_f32 v14, v8, v9
	v_cvt_pk_bf16_f32 v15, v10, v11
	ds_read_b128 v[8:11], v171 offset:49152
	global_store_dwordx2 v[12:13], v[14:15], off offset:32
	s_waitcnt lgkmcnt(0)
	v_pk_fma_f32 v[10:11], v[30:31], v[0:1], v[10:11] op_sel_hi:[1,0,1]
	v_pk_fma_f32 v[8:9], v[28:29], v[0:1], v[8:9] op_sel_hi:[1,0,1]
	s_nop 0
	v_cvt_pk_bf16_f32 v14, v8, v9
	v_cvt_pk_bf16_f32 v15, v10, v11
	ds_read_b128 v[8:11], v171 offset:57344
	global_store_dwordx2 v[12:13], v[14:15], off offset:64
	s_waitcnt lgkmcnt(0)
	v_pk_fma_f32 v[8:9], v[24:25], v[0:1], v[8:9] op_sel_hi:[1,0,1]
	v_pk_fma_f32 v[10:11], v[26:27], v[0:1], v[10:11] op_sel_hi:[1,0,1]
	v_cvt_pk_bf16_f32 v8, v8, v9
	s_nop 0
	v_cvt_pk_bf16_f32 v9, v10, v11
	global_store_dwordx2 v[12:13], v[8:9], off offset:96
	s_barrier

; __device__ __forceinline__ void nsa_phase(const Args& a, int l, int qslot, LAS unsigned char* lds, int tid, int lane, int wave) {
;     ...
;     for (;;) {
;         if (tid == 0) slot[0] = (int)atomicAdd(ctr, 1u);
;         __syncthreads();
;         const int u = slot[0];
;         __syncthreads();
;         if (u >= 512) break;
.LBB0_132:
	s_and_saveexec_b64 s[46:47], s[38:39]
	s_cbranch_execz .LBB0_136
	s_waitcnt vmcnt(8)
	v_readfirstlane_b32 s15, v249
	s_nop 3
	s_cmp_lg_u32 s15, -1
	s_cbranch_scc1 .Lq_have
	v_readlane_b32 s48, v255, 9
	v_readlane_b32 s49, v255, 10
	s_nop 4
	global_atomic_add v249, v1, v250, s[48:49] sc0
	s_waitcnt vmcnt(0)
.Lq_have:
	v_mov_b32_e32 v0, v249
	v_mov_b32_e32 v249, -1
	v_readlane_b32 s15, v254, 6
	s_nop 1
	v_mov_b32_e32 v8, s15
	ds_write_b32 v8, v0
